# gdn_local: chunk K.K^T / Q.K^T on the f32 matrix cores (v_mfma_f32_16x16x4_f32, f32 operands and accumulate) instead of the packed-f32 VALU loop
# speedup vs baseline: 1.5518x; 1.0105x over previous
.LBB0_366:
	s_or_b64 exec, exec, s[8:9]
	v_ashrrev_i32_e32 v35, 2, v0
	v_lshlrev_b32_e32 v4, 4, v0
	v_lshl_add_u32 v3, v35, 6, v35
	v_and_b32_e32 v4, 48, v4
	v_add_lshl_u32 v34, v3, v4, 2
	s_waitcnt lgkmcnt(0)
	s_barrier
	v_add_u32_e32 v58, 0x4100, v34
	v_add_u32_e32 v59, 0x4108, v34
	v_add_u32_e32 v60, 0x4110, v34
	v_add_u32_e32 v61, 0x4118, v34
	ds_read2_b32 v[4:5], v34 offset1:1
	ds_read2_b32 v[6:7], v34 offset0:2 offset1:3
	ds_read2_b32 v[8:9], v34 offset0:4 offset1:5
	ds_read2_b32 v[10:11], v34 offset0:6 offset1:7
	ds_read2_b32 v[12:13], v58 offset1:1
	ds_read2_b32 v[14:15], v59 offset1:1
	ds_read2_b32 v[16:17], v60 offset1:1
	ds_read2_b32 v[18:19], v61 offset1:1
	s_waitcnt lgkmcnt(7)
	v_mov_b32_e32 v27, v5
	s_waitcnt lgkmcnt(3)
	v_mov_b32_e32 v26, v13
	v_mov_b32_e32 v24, v12
	v_mov_b32_e32 v25, v4
	v_pk_mul_f32 v[26:27], v[26:27], v[26:27]
	s_waitcnt lgkmcnt(2)
	v_mov_b32_e32 v28, v15
	v_pk_fma_f32 v[24:25], v[24:25], v[24:25], v[26:27]
	v_mov_b32_e32 v26, v14
	v_mov_b32_e32 v27, v6
	v_mov_b32_e32 v29, v7
	v_pk_fma_f32 v[24:25], v[26:27], v[26:27], v[24:25]
	s_waitcnt lgkmcnt(1)
	v_mov_b32_e32 v26, v16
	v_pk_fma_f32 v[24:25], v[28:29], v[28:29], v[24:25]
	v_mov_b32_e32 v27, v8
	v_pk_mul_f32 v[20:21], v[10:11], v[10:11]
	s_waitcnt lgkmcnt(0)
	v_pk_mul_f32 v[22:23], v[18:19], v[18:19]
	v_mov_b32_e32 v28, v17
	v_mov_b32_e32 v29, v9
	v_pk_fma_f32 v[24:25], v[26:27], v[26:27], v[24:25]
	v_mov_b32_e32 v26, v22
	v_pk_fma_f32 v[24:25], v[28:29], v[28:29], v[24:25]
	v_mov_b32_e32 v27, v20
	v_pk_add_f32 v[24:25], v[24:25], v[26:27]
	v_mov_b32_e32 v20, v23
	v_add_u32_e32 v62, 0x4120, v34
	v_add_u32_e32 v63, 0x4128, v34
	v_pk_add_f32 v[20:21], v[24:25], v[20:21]
	ds_read2_b32 v[22:23], v34 offset0:8 offset1:9
	ds_read2_b32 v[24:25], v62 offset1:1
	ds_read2_b32 v[26:27], v34 offset0:10 offset1:11
	ds_read2_b32 v[28:29], v34 offset0:12 offset1:13
	ds_read2_b32 v[30:31], v34 offset0:14 offset1:15
	v_add_u32_e32 v64, 0x4130, v34
	v_add_u32_e32 v65, 0x4138, v34
	ds_read2_b32 v[36:37], v63 offset1:1
	ds_read2_b32 v[38:39], v64 offset1:1
	ds_read2_b32 v[40:41], v65 offset1:1
	s_waitcnt lgkmcnt(7)
	v_pk_mul_f32 v[32:33], v[22:23], v[22:23]
	s_waitcnt lgkmcnt(6)
	v_pk_mul_f32 v[42:43], v[24:25], v[24:25]
	v_mov_b32_e32 v57, v32
	v_mov_b32_e32 v56, v42
	s_waitcnt lgkmcnt(5)
	v_pk_mul_f32 v[44:45], v[26:27], v[26:27]
	s_waitcnt lgkmcnt(2)
	v_pk_mul_f32 v[46:47], v[36:37], v[36:37]
	v_pk_add_f32 v[20:21], v[20:21], v[56:57]
	v_mov_b32_e32 v32, v43
	v_pk_add_f32 v[20:21], v[20:21], v[32:33]
	v_mov_b32_e32 v32, v46
	v_mov_b32_e32 v33, v44
	v_pk_mul_f32 v[48:49], v[28:29], v[28:29]
	s_waitcnt lgkmcnt(1)
	v_pk_mul_f32 v[50:51], v[38:39], v[38:39]
	v_pk_add_f32 v[20:21], v[20:21], v[32:33]
	v_mov_b32_e32 v44, v47
	v_pk_add_f32 v[20:21], v[20:21], v[44:45]
	v_mov_b32_e32 v32, v50
	v_mov_b32_e32 v33, v48
	v_xor_b32_e32 v3, 1, v2
	v_add_u32_e32 v66, 64, v1
	v_pk_mul_f32 v[52:53], v[30:31], v[30:31]
	s_waitcnt lgkmcnt(0)
	v_pk_mul_f32 v[54:55], v[40:41], v[40:41]
	v_pk_add_f32 v[20:21], v[20:21], v[32:33]
	v_mov_b32_e32 v48, v51
	v_cmp_lt_i32_e32 vcc, v3, v66
	v_pk_add_f32 v[20:21], v[20:21], v[48:49]
	v_mov_b32_e32 v32, v54
	v_mov_b32_e32 v33, v52
	v_cndmask_b32_e32 v1, v2, v3, vcc
	v_pk_add_f32 v[20:21], v[20:21], v[32:33]
	v_mov_b32_e32 v52, v55
	v_lshlrev_b32_e32 v1, 2, v1
	v_pk_add_f32 v[20:21], v[20:21], v[52:53]
	ds_bpermute_b32 v33, v1, v21
	ds_bpermute_b32 v32, v1, v20
	v_xor_b32_e32 v3, 2, v2
	v_cmp_lt_i32_e32 vcc, v3, v66
	s_mov_b32 s0, 0x358637bd
	s_nop 0
	v_cndmask_b32_e32 v2, v2, v3, vcc
	v_lshlrev_b32_e32 v42, 2, v2
	s_waitcnt lgkmcnt(0)
	v_pk_add_f32 v[2:3], v[20:21], v[32:33]
	ds_bpermute_b32 v21, v42, v3
	ds_bpermute_b32 v20, v42, v2
	s_waitcnt lgkmcnt(0)
	v_pk_add_f32 v[2:3], v[2:3], v[20:21]
	s_nop 0
	v_pk_add_f32 v[2:3], v[2:3], s[0:1] op_sel_hi:[1,0]
	s_nop 0
	v_mul_f32_e32 v20, 0x4b800000, v3
	v_cmp_gt_f32_e32 vcc, s49, v3
	s_nop 1
	v_cndmask_b32_e32 v3, v3, v20, vcc
	v_rsq_f32_e32 v3, v3
	s_nop 0
	v_mul_f32_e32 v20, 0x45800000, v3
	v_cndmask_b32_e32 v3, v3, v20, vcc
	v_mul_f32_e32 v20, 0x3e000000, v3
	v_mul_f32_e32 v3, 0x4b800000, v2
	v_cmp_gt_f32_e32 vcc, s49, v2
	v_pk_mul_f32 v[4:5], v[4:5], v[20:21] op_sel_hi:[1,0]
	ds_write2_b32 v34, v4, v5 offset1:1
	v_cndmask_b32_e32 v2, v2, v3, vcc
	v_pk_mul_f32 v[4:5], v[6:7], v[20:21] op_sel_hi:[1,0]
	v_rsq_f32_e32 v6, v2
	ds_write2_b32 v34, v4, v5 offset0:2 offset1:3
	v_pk_mul_f32 v[4:5], v[8:9], v[20:21] op_sel_hi:[1,0]
	ds_write2_b32 v34, v4, v5 offset0:4 offset1:5
	v_pk_mul_f32 v[4:5], v[10:11], v[20:21] op_sel_hi:[1,0]
	ds_write2_b32 v34, v4, v5 offset0:6 offset1:7
	v_pk_mul_f32 v[4:5], v[22:23], v[20:21] op_sel_hi:[1,0]
	v_pk_mul_f32 v[2:3], v[30:31], v[20:21] op_sel_hi:[1,0]
	ds_write2_b32 v34, v4, v5 offset0:8 offset1:9
	v_pk_mul_f32 v[4:5], v[26:27], v[20:21] op_sel_hi:[1,0]
	ds_write2_b32 v34, v2, v3 offset0:14 offset1:15
	v_mul_f32_e32 v2, 0x45800000, v6
	ds_write2_b32 v34, v4, v5 offset0:10 offset1:11
	v_pk_mul_f32 v[4:5], v[28:29], v[20:21] op_sel_hi:[1,0]
	v_cndmask_b32_e32 v2, v6, v2, vcc
	ds_write2_b32 v34, v4, v5 offset0:12 offset1:13
	v_pk_mul_f32 v[4:5], v[12:13], v[2:3] op_sel_hi:[1,0]
	ds_write2_b32 v58, v4, v5 offset1:1
	v_pk_mul_f32 v[4:5], v[14:15], v[2:3] op_sel_hi:[1,0]
	ds_write2_b32 v59, v4, v5 offset1:1
	v_pk_mul_f32 v[4:5], v[16:17], v[2:3] op_sel_hi:[1,0]
	ds_write2_b32 v60, v4, v5 offset1:1
	v_pk_mul_f32 v[4:5], v[18:19], v[2:3] op_sel_hi:[1,0]
	ds_write2_b32 v61, v4, v5 offset1:1
	v_pk_mul_f32 v[4:5], v[24:25], v[2:3] op_sel_hi:[1,0]
	ds_write2_b32 v62, v4, v5 offset1:1
	v_pk_mul_f32 v[4:5], v[36:37], v[2:3] op_sel_hi:[1,0]
	ds_write2_b32 v63, v4, v5 offset1:1
	v_pk_mul_f32 v[4:5], v[38:39], v[2:3] op_sel_hi:[1,0]
	v_pk_mul_f32 v[2:3], v[40:41], v[2:3] op_sel_hi:[1,0]
	v_ashrrev_i32_e32 v34, 4, v0
	v_and_b32_e32 v36, 15, v0
	v_mov_b32_e32 v7, 0
	ds_write2_b32 v64, v4, v5 offset1:1
	ds_write2_b32 v65, v2, v3 offset1:1
	v_cmp_le_i32_e32 vcc, v36, v34
	v_mov_b32_e32 v6, v7
	v_mov_b32_e32 v9, v7
	v_mov_b32_e32 v8, v7
	v_mov_b32_e32 v15, v7
	v_mov_b32_e32 v14, v7
	v_mov_b32_e32 v17, v7
	v_mov_b32_e32 v16, v7
	v_mov_b32_e32 v23, v7
	v_mov_b32_e32 v22, v7
	v_mov_b32_e32 v25, v7
	v_mov_b32_e32 v24, v7
	v_mov_b32_e32 v27, v7
	v_mov_b32_e32 v26, v7
	v_mov_b32_e32 v29, v7
	v_mov_b32_e32 v28, v7
	v_mov_b32_e32 v19, v7
	v_mov_b32_e32 v18, v7
	v_mov_b32_e32 v21, v7
	v_mov_b32_e32 v20, v7
	v_mov_b32_e32 v11, v7
	v_mov_b32_e32 v10, v7
	v_mov_b32_e32 v13, v7
	v_mov_b32_e32 v12, v7
	v_mov_b32_e32 v3, v7
	v_mov_b32_e32 v2, v7
	v_mov_b32_e32 v5, v7
	v_mov_b32_e32 v4, v7
	v_mov_b32_e32 v33, v7
	v_mov_b32_e32 v32, v7
	v_mov_b32_e32 v31, v7
	v_mov_b32_e32 v30, v7
	s_waitcnt lgkmcnt(0)
	s_barrier
	v_lshrrev_b32_e32 v1, 6, v182
	v_and_b32_e32 v37, 15, v182
	v_bfe_u32 v38, v182, 4, 2
	v_mul_u32_u24_e32 v40, 0x104, v37
	v_readfirstlane_b32 s0, v1
	v_lshl_add_u32 v40, v38, 2, v40
	v_mul_u32_u24_e32 v43, 0x1040, v1
	v_add_u32_e32 v44, v43, v40
	v_add_u32_e32 v45, 0x4100, v44
	ds_read2_b32 v[136:137], v45 offset0:0 offset1:4
	ds_read2_b32 v[138:139], v45 offset0:8 offset1:12
	ds_read2_b32 v[140:141], v45 offset0:16 offset1:20
	ds_read2_b32 v[142:143], v45 offset0:24 offset1:28
	ds_read2_b32 v[144:145], v45 offset0:32 offset1:36
	ds_read2_b32 v[146:147], v45 offset0:40 offset1:44
	ds_read2_b32 v[148:149], v45 offset0:48 offset1:52
	ds_read2_b32 v[150:151], v45 offset0:56 offset1:60
	ds_read2_b32 v[152:153], v44 offset0:0 offset1:4
	ds_read2_b32 v[154:155], v44 offset0:8 offset1:12
	ds_read2_b32 v[156:157], v44 offset0:16 offset1:20
	ds_read2_b32 v[158:159], v44 offset0:24 offset1:28
	ds_read2_b32 v[160:161], v44 offset0:32 offset1:36
	ds_read2_b32 v[162:163], v44 offset0:40 offset1:44
	ds_read2_b32 v[164:165], v44 offset0:48 offset1:52
	ds_read2_b32 v[166:167], v44 offset0:56 offset1:60
	v_lshlrev_b32_e32 v46, 12, v1
	v_lshl_add_u32 v46, v38, 10, v46
	v_add_u32_e32 v46, 0xc300, v46
	v_lshl_add_u32 v48, v37, 2, v46
	v_lshl_add_u32 v51, v37, 4, v46
	v_lshlrev_b32_e32 v53, 6, v1
	s_mov_b64 s[8:9], exec
	s_waitcnt lgkmcnt(0)
	v_mfma_f32_16x16x4_f32 v[210:213], v136, v136, 0
	v_mfma_f32_16x16x4_f32 v[214:217], v152, v136, 0
	v_mfma_f32_16x16x4_f32 v[210:213], v137, v137, v[210:213]
	v_mfma_f32_16x16x4_f32 v[214:217], v153, v137, v[214:217]
	v_mfma_f32_16x16x4_f32 v[210:213], v138, v138, v[210:213]
	v_mfma_f32_16x16x4_f32 v[214:217], v154, v138, v[214:217]
	v_mfma_f32_16x16x4_f32 v[210:213], v139, v139, v[210:213]
	v_mfma_f32_16x16x4_f32 v[214:217], v155, v139, v[214:217]
	v_mfma_f32_16x16x4_f32 v[210:213], v140, v140, v[210:213]
	v_mfma_f32_16x16x4_f32 v[214:217], v156, v140, v[214:217]
	v_mfma_f32_16x16x4_f32 v[210:213], v141, v141, v[210:213]
	v_mfma_f32_16x16x4_f32 v[214:217], v157, v141, v[214:217]
	v_mfma_f32_16x16x4_f32 v[210:213], v142, v142, v[210:213]
	v_mfma_f32_16x16x4_f32 v[214:217], v158, v142, v[214:217]
	v_mfma_f32_16x16x4_f32 v[210:213], v143, v143, v[210:213]
	v_mfma_f32_16x16x4_f32 v[214:217], v159, v143, v[214:217]
	v_mfma_f32_16x16x4_f32 v[210:213], v144, v144, v[210:213]
	v_mfma_f32_16x16x4_f32 v[214:217], v160, v144, v[214:217]
	v_mfma_f32_16x16x4_f32 v[210:213], v145, v145, v[210:213]
	v_mfma_f32_16x16x4_f32 v[214:217], v161, v145, v[214:217]
	v_mfma_f32_16x16x4_f32 v[210:213], v146, v146, v[210:213]
	v_mfma_f32_16x16x4_f32 v[214:217], v162, v146, v[214:217]
	v_mfma_f32_16x16x4_f32 v[210:213], v147, v147, v[210:213]
	v_mfma_f32_16x16x4_f32 v[214:217], v163, v147, v[214:217]
	v_mfma_f32_16x16x4_f32 v[210:213], v148, v148, v[210:213]
	v_mfma_f32_16x16x4_f32 v[214:217], v164, v148, v[214:217]
	v_mfma_f32_16x16x4_f32 v[210:213], v149, v149, v[210:213]
	v_mfma_f32_16x16x4_f32 v[214:217], v165, v149, v[214:217]
	v_mfma_f32_16x16x4_f32 v[210:213], v150, v150, v[210:213]
	v_mfma_f32_16x16x4_f32 v[214:217], v166, v150, v[214:217]
	v_mfma_f32_16x16x4_f32 v[210:213], v151, v151, v[210:213]
	v_mfma_f32_16x16x4_f32 v[214:217], v167, v151, v[214:217]
	s_cmp_lt_u32 s0, 1
	s_cbranch_scc1 .Lkkqk_md
	v_add_u32_e32 v52, 0xffffefc0, v45
	ds_read2_b32 v[168:169], v52 offset0:0 offset1:4
	ds_read2_b32 v[170:171], v52 offset0:8 offset1:12
	ds_read2_b32 v[172:173], v52 offset0:16 offset1:20
	ds_read2_b32 v[174:175], v52 offset0:24 offset1:28
	ds_read2_b32 v[176:177], v52 offset0:32 offset1:36
	ds_read2_b32 v[178:179], v52 offset0:40 offset1:44
	ds_read2_b32 v[180:181], v52 offset0:48 offset1:52
	ds_read2_b32 v[64:65], v52 offset0:56 offset1:60
	s_waitcnt lgkmcnt(0)
	v_mfma_f32_16x16x4_f32 v[224:227], v136, v168, 0
	v_mfma_f32_16x16x4_f32 v[228:231], v152, v168, 0
	v_mfma_f32_16x16x4_f32 v[224:227], v137, v169, v[224:227]
	v_mfma_f32_16x16x4_f32 v[228:231], v153, v169, v[228:231]
	v_mfma_f32_16x16x4_f32 v[224:227], v138, v170, v[224:227]
	v_mfma_f32_16x16x4_f32 v[228:231], v154, v170, v[228:231]
	v_mfma_f32_16x16x4_f32 v[224:227], v139, v171, v[224:227]
	v_mfma_f32_16x16x4_f32 v[228:231], v155, v171, v[228:231]
	v_mfma_f32_16x16x4_f32 v[224:227], v140, v172, v[224:227]
	v_mfma_f32_16x16x4_f32 v[228:231], v156, v172, v[228:231]
	v_mfma_f32_16x16x4_f32 v[224:227], v141, v173, v[224:227]
	v_mfma_f32_16x16x4_f32 v[228:231], v157, v173, v[228:231]
	v_mfma_f32_16x16x4_f32 v[224:227], v142, v174, v[224:227]
	v_mfma_f32_16x16x4_f32 v[228:231], v158, v174, v[228:231]
	v_mfma_f32_16x16x4_f32 v[224:227], v143, v175, v[224:227]
	v_mfma_f32_16x16x4_f32 v[228:231], v159, v175, v[228:231]
	v_mfma_f32_16x16x4_f32 v[224:227], v144, v176, v[224:227]
	v_mfma_f32_16x16x4_f32 v[228:231], v160, v176, v[228:231]
	v_mfma_f32_16x16x4_f32 v[224:227], v145, v177, v[224:227]
	v_mfma_f32_16x16x4_f32 v[228:231], v161, v177, v[228:231]
	v_mfma_f32_16x16x4_f32 v[224:227], v146, v178, v[224:227]
	v_mfma_f32_16x16x4_f32 v[228:231], v162, v178, v[228:231]
	v_mfma_f32_16x16x4_f32 v[224:227], v147, v179, v[224:227]
	v_mfma_f32_16x16x4_f32 v[228:231], v163, v179, v[228:231]
	v_mfma_f32_16x16x4_f32 v[224:227], v148, v180, v[224:227]
	v_mfma_f32_16x16x4_f32 v[228:231], v164, v180, v[228:231]
	v_mfma_f32_16x16x4_f32 v[224:227], v149, v181, v[224:227]
	v_mfma_f32_16x16x4_f32 v[228:231], v165, v181, v[228:231]
	v_mfma_f32_16x16x4_f32 v[224:227], v150, v64, v[224:227]
	v_mfma_f32_16x16x4_f32 v[228:231], v166, v64, v[228:231]
	v_mfma_f32_16x16x4_f32 v[224:227], v151, v65, v[224:227]
	v_mfma_f32_16x16x4_f32 v[228:231], v167, v65, v[228:231]
	s_cmp_lt_u32 s0, 2
	s_cbranch_scc1 .Lkkqk_md
	v_add_u32_e32 v52, 0xffffdf80, v45
	ds_read2_b32 v[168:169], v52 offset0:0 offset1:4
	ds_read2_b32 v[170:171], v52 offset0:8 offset1:12
	ds_read2_b32 v[172:173], v52 offset0:16 offset1:20
	ds_read2_b32 v[174:175], v52 offset0:24 offset1:28
	ds_read2_b32 v[176:177], v52 offset0:32 offset1:36
	ds_read2_b32 v[178:179], v52 offset0:40 offset1:44
	ds_read2_b32 v[180:181], v52 offset0:48 offset1:52
	ds_read2_b32 v[64:65], v52 offset0:56 offset1:60
	s_waitcnt lgkmcnt(0)
	v_mfma_f32_16x16x4_f32 v[234:237], v136, v168, 0
	v_mfma_f32_16x16x4_f32 v[238:241], v152, v168, 0
	v_mfma_f32_16x16x4_f32 v[234:237], v137, v169, v[234:237]
	v_mfma_f32_16x16x4_f32 v[238:241], v153, v169, v[238:241]
	v_mfma_f32_16x16x4_f32 v[234:237], v138, v170, v[234:237]
	v_mfma_f32_16x16x4_f32 v[238:241], v154, v170, v[238:241]
	v_mfma_f32_16x16x4_f32 v[234:237], v139, v171, v[234:237]
	v_mfma_f32_16x16x4_f32 v[238:241], v155, v171, v[238:241]
	v_mfma_f32_16x16x4_f32 v[234:237], v140, v172, v[234:237]
	v_mfma_f32_16x16x4_f32 v[238:241], v156, v172, v[238:241]
	v_mfma_f32_16x16x4_f32 v[234:237], v141, v173, v[234:237]
	v_mfma_f32_16x16x4_f32 v[238:241], v157, v173, v[238:241]
	v_mfma_f32_16x16x4_f32 v[234:237], v142, v174, v[234:237]
	v_mfma_f32_16x16x4_f32 v[238:241], v158, v174, v[238:241]
	v_mfma_f32_16x16x4_f32 v[234:237], v143, v175, v[234:237]
	v_mfma_f32_16x16x4_f32 v[238:241], v159, v175, v[238:241]
	v_mfma_f32_16x16x4_f32 v[234:237], v144, v176, v[234:237]
	v_mfma_f32_16x16x4_f32 v[238:241], v160, v176, v[238:241]
	v_mfma_f32_16x16x4_f32 v[234:237], v145, v177, v[234:237]
	v_mfma_f32_16x16x4_f32 v[238:241], v161, v177, v[238:241]
	v_mfma_f32_16x16x4_f32 v[234:237], v146, v178, v[234:237]
	v_mfma_f32_16x16x4_f32 v[238:241], v162, v178, v[238:241]
	v_mfma_f32_16x16x4_f32 v[234:237], v147, v179, v[234:237]
	v_mfma_f32_16x16x4_f32 v[238:241], v163, v179, v[238:241]
	v_mfma_f32_16x16x4_f32 v[234:237], v148, v180, v[234:237]
	v_mfma_f32_16x16x4_f32 v[238:241], v164, v180, v[238:241]
	v_mfma_f32_16x16x4_f32 v[234:237], v149, v181, v[234:237]
	v_mfma_f32_16x16x4_f32 v[238:241], v165, v181, v[238:241]
	v_mfma_f32_16x16x4_f32 v[234:237], v150, v64, v[234:237]
	v_mfma_f32_16x16x4_f32 v[238:241], v166, v64, v[238:241]
	v_mfma_f32_16x16x4_f32 v[234:237], v151, v65, v[234:237]
	v_mfma_f32_16x16x4_f32 v[238:241], v167, v65, v[238:241]
	s_cmp_lt_u32 s0, 3
	s_cbranch_scc1 .Lkkqk_md
	v_add_u32_e32 v52, 0xffffcf40, v45
	ds_read2_b32 v[168:169], v52 offset0:0 offset1:4
	ds_read2_b32 v[170:171], v52 offset0:8 offset1:12
	ds_read2_b32 v[172:173], v52 offset0:16 offset1:20
	ds_read2_b32 v[174:175], v52 offset0:24 offset1:28
	ds_read2_b32 v[176:177], v52 offset0:32 offset1:36
	ds_read2_b32 v[178:179], v52 offset0:40 offset1:44
	ds_read2_b32 v[180:181], v52 offset0:48 offset1:52
	ds_read2_b32 v[64:65], v52 offset0:56 offset1:60
	s_waitcnt lgkmcnt(0)
	v_mfma_f32_16x16x4_f32 v[242:245], v136, v168, 0
	v_mfma_f32_16x16x4_f32 v[60:63], v152, v168, 0
	v_mfma_f32_16x16x4_f32 v[242:245], v137, v169, v[242:245]
	v_mfma_f32_16x16x4_f32 v[60:63], v153, v169, v[60:63]
	v_mfma_f32_16x16x4_f32 v[242:245], v138, v170, v[242:245]
	v_mfma_f32_16x16x4_f32 v[60:63], v154, v170, v[60:63]
	v_mfma_f32_16x16x4_f32 v[242:245], v139, v171, v[242:245]
	v_mfma_f32_16x16x4_f32 v[60:63], v155, v171, v[60:63]
	v_mfma_f32_16x16x4_f32 v[242:245], v140, v172, v[242:245]
	v_mfma_f32_16x16x4_f32 v[60:63], v156, v172, v[60:63]
	v_mfma_f32_16x16x4_f32 v[242:245], v141, v173, v[242:245]
	v_mfma_f32_16x16x4_f32 v[60:63], v157, v173, v[60:63]
	v_mfma_f32_16x16x4_f32 v[242:245], v142, v174, v[242:245]
	v_mfma_f32_16x16x4_f32 v[60:63], v158, v174, v[60:63]
	v_mfma_f32_16x16x4_f32 v[242:245], v143, v175, v[242:245]
	v_mfma_f32_16x16x4_f32 v[60:63], v159, v175, v[60:63]
	v_mfma_f32_16x16x4_f32 v[242:245], v144, v176, v[242:245]
	v_mfma_f32_16x16x4_f32 v[60:63], v160, v176, v[60:63]
	v_mfma_f32_16x16x4_f32 v[242:245], v145, v177, v[242:245]
	v_mfma_f32_16x16x4_f32 v[60:63], v161, v177, v[60:63]
	v_mfma_f32_16x16x4_f32 v[242:245], v146, v178, v[242:245]
	v_mfma_f32_16x16x4_f32 v[60:63], v162, v178, v[60:63]
	v_mfma_f32_16x16x4_f32 v[242:245], v147, v179, v[242:245]
	v_mfma_f32_16x16x4_f32 v[60:63], v163, v179, v[60:63]
	v_mfma_f32_16x16x4_f32 v[242:245], v148, v180, v[242:245]
	v_mfma_f32_16x16x4_f32 v[60:63], v164, v180, v[60:63]
	v_mfma_f32_16x16x4_f32 v[242:245], v149, v181, v[242:245]
	v_mfma_f32_16x16x4_f32 v[60:63], v165, v181, v[60:63]
	v_mfma_f32_16x16x4_f32 v[242:245], v150, v64, v[242:245]
	v_mfma_f32_16x16x4_f32 v[60:63], v166, v64, v[60:63]
	v_mfma_f32_16x16x4_f32 v[242:245], v151, v65, v[242:245]
	v_mfma_f32_16x16x4_f32 v[60:63], v167, v65, v[60:63]
.Lkkqk_md:
	s_nop 7
	s_nop 3
	v_add_u32_e32 v54, v48, v53
	ds_write_b32 v54, v210 offset:0
	ds_write_b32 v54, v211 offset:256
	ds_write_b32 v54, v212 offset:512
	ds_write_b32 v54, v213 offset:768
	s_cmp_lt_u32 s0, 1
	s_cbranch_scc1 .Lkkqk_k_w
	v_add_u32_e32 v54, v48, v53
	v_add_u32_e32 v54, 0xffffffc0, v54
	ds_write_b32 v54, v224 offset:0
	ds_write_b32 v54, v225 offset:256
	ds_write_b32 v54, v226 offset:512
	ds_write_b32 v54, v227 offset:768
	s_cmp_lt_u32 s0, 2
	s_cbranch_scc1 .Lkkqk_k_w
	v_add_u32_e32 v54, v48, v53
	v_add_u32_e32 v54, 0xffffff80, v54
	ds_write_b32 v54, v234 offset:0
	ds_write_b32 v54, v235 offset:256
	ds_write_b32 v54, v236 offset:512
	ds_write_b32 v54, v237 offset:768
	s_cmp_lt_u32 s0, 3
	s_cbranch_scc1 .Lkkqk_k_w
	v_add_u32_e32 v54, v48, v53
	v_add_u32_e32 v54, 0xffffff40, v54
	ds_write_b32 v54, v242 offset:0
	ds_write_b32 v54, v243 offset:256
	ds_write_b32 v54, v244 offset:512
	ds_write_b32 v54, v245 offset:768
.Lkkqk_k_w:
	s_cmp_gt_u32 s0, 2
	s_cbranch_scc1 .Lkkqk_k_z
	v_add_u32_e32 v54, v48, v53
	v_add_u32_e32 v54, 0x40, v54
	ds_write_b32 v54, v113 offset:0
	ds_write_b32 v54, v113 offset:256
	ds_write_b32 v54, v113 offset:512
	ds_write_b32 v54, v113 offset:768
	s_cmp_gt_u32 s0, 1
	s_cbranch_scc1 .Lkkqk_k_z
	v_add_u32_e32 v54, v48, v53
	v_add_u32_e32 v54, 0x80, v54
	ds_write_b32 v54, v113 offset:0
	ds_write_b32 v54, v113 offset:256
	ds_write_b32 v54, v113 offset:512
	ds_write_b32 v54, v113 offset:768
	s_cmp_gt_u32 s0, 0
	s_cbranch_scc1 .Lkkqk_k_z
	v_add_u32_e32 v54, v48, v53
	v_add_u32_e32 v54, 0xc0, v54
	ds_write_b32 v54, v113 offset:0
	ds_write_b32 v54, v113 offset:256
	ds_write_b32 v54, v113 offset:512
	ds_write_b32 v54, v113 offset:768
.Lkkqk_k_z:
	s_waitcnt lgkmcnt(0)
	ds_read_b64 v[32:33], v51 offset:0
	ds_read_b64 v[30:31], v51 offset:8
	ds_read_b64 v[56:57], v51 offset:256
	ds_read_b64 v[22:23], v51 offset:264
	ds_read_b64 v[58:59], v51 offset:512
	ds_read_b64 v[14:15], v51 offset:520
	ds_read_b64 v[8:9], v51 offset:768
	ds_read_b64 v[6:7], v51 offset:776
	s_waitcnt lgkmcnt(0)
	v_mov_b32_e32 v25, v56
	v_mov_b32_e32 v24, v57
	v_mov_b32_e32 v17, v58
	v_mov_b32_e32 v16, v59
	v_add_u32_e32 v54, v48, v53
	ds_write_b32 v54, v214 offset:0
	ds_write_b32 v54, v215 offset:256
	ds_write_b32 v54, v216 offset:512
	ds_write_b32 v54, v217 offset:768
	s_cmp_lt_u32 s0, 1
	s_cbranch_scc1 .Lkkqk_q_w
	v_add_u32_e32 v54, v48, v53
	v_add_u32_e32 v54, 0xffffffc0, v54
	ds_write_b32 v54, v228 offset:0
	ds_write_b32 v54, v229 offset:256
	ds_write_b32 v54, v230 offset:512
	ds_write_b32 v54, v231 offset:768
	s_cmp_lt_u32 s0, 2
	s_cbranch_scc1 .Lkkqk_q_w
	v_add_u32_e32 v54, v48, v53
	v_add_u32_e32 v54, 0xffffff80, v54
	ds_write_b32 v54, v238 offset:0
	ds_write_b32 v54, v239 offset:256
	ds_write_b32 v54, v240 offset:512
	ds_write_b32 v54, v241 offset:768
	s_cmp_lt_u32 s0, 3
	s_cbranch_scc1 .Lkkqk_q_w
	v_add_u32_e32 v54, v48, v53
	v_add_u32_e32 v54, 0xffffff40, v54
	ds_write_b32 v54, v60 offset:0
	ds_write_b32 v54, v61 offset:256
	ds_write_b32 v54, v62 offset:512
	ds_write_b32 v54, v63 offset:768

.Lkkqk_q_z:
	s_waitcnt lgkmcnt(0)
	ds_read_b64 v[26:27], v51 offset:0
	ds_read_b64 v[28:29], v51 offset:8
	ds_read_b64 v[18:19], v51 offset:256
	ds_read_b64 v[20:21], v51 offset:264
	ds_read_b64 v[10:11], v51 offset:512
	ds_read_b64 v[12:13], v51 offset:520
	ds_read_b64 v[2:3], v51 offset:768
	ds_read_b64 v[4:5], v51 offset:776
	s_waitcnt lgkmcnt(0)
